# branch GEMM: prefetch the WG's three branch-gate byte planes (G8) toward the memory-side cache at phase start, on top of the handover variant
# speedup vs baseline: 1.0016x; 1.0016x over previous
.LBB0_726:
	s_add_u32 s68, s16, 0x53a00000
	s_addc_u32 s69, s17, 0
	s_add_u32 s20, s16, 0x43c00000
	v_lshrrev_b32_e32 v19, 1, v3
	s_addc_u32 s21, s17, 0
	v_and_b32_e32 v19, 24, v19
	s_add_u32 s77, s16, 0x47100000
	v_and_b32_e32 v18, 15, v3
	v_lshlrev_b32_e32 v20, 1, v19
	v_lshlrev_b32_e32 v3, 2, v3
	s_addc_u32 s78, s17, 0
	v_lshl_or_b32 v236, s6, 6, v18
	v_lshl_or_b32 v18, v18, 6, v20
	s_lshl_b32 s6, s6, 13
	v_and_b32_e32 v3, 32, v3
	v_bitop3_b32 v20, v18, s6, v3 bitop3:0xde
	s_lshl_b32 s6, s13, 5
	s_and_b32 s6, s6, 0x60
	s_add_i32 m0, s52, 0x18000
	v_lshl_add_u64 v[10:11], v[10:11], 0, s[90:91]
	s_lshl_b32 s10, s6, 7
	s_waitcnt vmcnt(2)
	s_barrier
	global_load_lds_dwordx4 v[10:11], off
	v_lshl_add_u64 v[8:9], v[8:9], 0, s[90:91]
	s_add_i32 m0, s52, 0x1a000
	s_add_i32 s80, s52, 0x8000
	s_add_i32 s81, s52, 0xa000
	v_bitop3_b32 v237, v18, s10, v3 bitop3:0xde
	global_load_lds_dwordx4 v[8:9], off
	v_lshl_add_u64 v[4:5], v[4:5], 0, s[90:91]
	s_mov_b32 m0, s80
	s_add_u32 s10, s36, 0x40080
	global_load_lds_dwordx4 v[4:5], off
	v_lshl_add_u64 v[4:5], v[6:7], 0, s[90:91]
	s_mov_b32 m0, s81
	s_addc_u32 s11, s37, 0
	global_load_lds_dwordx4 v[4:5], off
	s_add_i32 m0, s52, 0x1c000
	v_lshl_add_u64 v[4:5], s[10:11], 0, v[136:137]
	global_load_lds_dwordx4 v[4:5], off
	v_lshl_add_u64 v[4:5], s[10:11], 0, v[140:141]
	s_add_i32 m0, s52, 0x1e000
	s_cmpk_lt_u32 s4, 0x100
	global_load_lds_dwordx4 v[4:5], off
	s_cselect_b64 s[22:23], -1, 0
	s_abs_i32 s4, s26
	v_cvt_f32_u32_e32 v3, s4
	v_or_b32_e32 v248, s6, v19
	s_ashr_i32 s6, s26, 31
	v_readlane_b32 s10, v254, 58
	v_rcp_iflag_f32_e32 v3, v3
	s_xor_b32 s6, s10, s6
	s_sub_i32 s10, 0, s4
	v_readlane_b32 s13, v254, 59
	v_mul_f32_e32 v3, 0x4f7ffffe, v3
	v_cvt_u32_f32_e32 v3, v3
	v_and_b32_e32 v4, 1, v12
	s_waitcnt vmcnt(6)
	v_mov_b32_e32 v5, v2
	v_readfirstlane_b32 s11, v3
	s_mul_i32 s10, s10, s11
	s_mul_hi_u32 s10, s11, s10
	s_add_i32 s11, s11, s10
	s_mul_hi_u32 s10, s13, s11
	s_mul_i32 s11, s10, s4
	s_sub_i32 s11, s13, s11
	s_add_i32 s13, s10, 1
	s_sub_i32 s15, s11, s4
	v_lshlrev_b32_e32 v3, 14, v12
	s_cmp_ge_u32 s11, s4
	v_and_b32_e32 v3, 0xffff8000, v3
	s_cselect_b32 s10, s13, s10
	v_lshl_add_u32 v3, v13, 11, v3
	s_cselect_b32 s11, s15, s11
	s_add_i32 s13, s10, 1
	v_lshl_or_b32 v3, v4, 6, v3
	s_cmp_ge_u32 s11, s4
	v_lshl_add_u32 v142, v14, 1, v3
	v_lshlrev_b32_e32 v3, 14, v15
	s_cselect_b32 s4, s13, s10
	v_and_b32_e32 v3, 0xffff8000, v3
	s_xor_b32 s4, s4, s6
	v_lshl_add_u32 v3, v16, 11, v3
	v_and_b32_e32 v4, 1, v15
	s_sub_i32 s4, s4, s6
	v_lshl_or_b32 v3, v4, 6, v3
	v_mov_b32_e32 v4, v2
	s_mul_i32 s4, s4, 3
	v_lshl_add_u32 v144, v17, 1, v3
	v_mov_b32_e32 v3, v2
	v_add_u32_e32 v249, 0, v20
	v_mov_b64_e32 v[8:9], v[4:5]
	v_mov_b64_e32 v[12:13], v[4:5]
	v_mov_b64_e32 v[16:17], v[4:5]
	v_mov_b64_e32 v[20:21], v[4:5]
	v_mov_b64_e32 v[24:25], v[4:5]
	v_mov_b64_e32 v[28:29], v[4:5]
	v_mov_b64_e32 v[32:33], v[4:5]
	v_mov_b64_e32 v[36:37], v[4:5]
	v_mov_b64_e32 v[40:41], v[4:5]
	v_mov_b64_e32 v[44:45], v[4:5]
	v_mov_b64_e32 v[48:49], v[4:5]
	v_mov_b64_e32 v[52:53], v[4:5]
	v_mov_b64_e32 v[56:57], v[4:5]
	v_mov_b64_e32 v[60:61], v[4:5]
	v_mov_b64_e32 v[64:65], v[4:5]
	v_mov_b64_e32 v[68:69], v[4:5]
	v_mov_b64_e32 v[72:73], v[4:5]
	s_waitcnt vmcnt(0)
	v_mov_b64_e32 v[76:77], v[4:5]
	v_mov_b64_e32 v[80:81], v[4:5]
	v_mov_b64_e32 v[84:85], v[4:5]
	v_mov_b64_e32 v[88:89], v[4:5]
	v_mov_b64_e32 v[92:93], v[4:5]
	v_mov_b64_e32 v[96:97], v[4:5]
	v_mov_b64_e32 v[100:101], v[4:5]
	v_mov_b64_e32 v[104:105], v[4:5]
	v_mov_b64_e32 v[108:109], v[4:5]
	v_mov_b64_e32 v[112:113], v[4:5]
	v_mov_b64_e32 v[116:117], v[4:5]
	v_mov_b64_e32 v[120:121], v[4:5]
	v_mov_b64_e32 v[124:125], v[4:5]
	v_mov_b64_e32 v[128:129], v[4:5]
	v_mov_b64_e32 v[132:133], v[4:5]
	s_mov_b32 s51, 0
	s_add_i32 s4, s4, 3
	v_mov_b32_e32 v143, v2
	v_mov_b32_e32 v145, v2
	v_mov_b32_e32 v251, s0
	v_mov_b64_e32 v[6:7], v[2:3]
	v_mov_b64_e32 v[10:11], v[2:3]
	v_mov_b64_e32 v[14:15], v[2:3]
	v_mov_b64_e32 v[18:19], v[2:3]
	v_mov_b64_e32 v[22:23], v[2:3]
	v_mov_b64_e32 v[26:27], v[2:3]
	v_mov_b64_e32 v[30:31], v[2:3]
	v_mov_b64_e32 v[34:35], v[2:3]
	v_mov_b64_e32 v[38:39], v[2:3]
	v_mov_b64_e32 v[42:43], v[2:3]
	v_mov_b64_e32 v[46:47], v[2:3]
	v_mov_b64_e32 v[50:51], v[2:3]
	v_mov_b64_e32 v[54:55], v[2:3]
	v_mov_b64_e32 v[58:59], v[2:3]
	v_mov_b64_e32 v[62:63], v[2:3]
	v_mov_b64_e32 v[66:67], v[2:3]
	v_mov_b64_e32 v[70:71], v[2:3]
	v_mov_b64_e32 v[74:75], v[2:3]
	v_mov_b64_e32 v[78:79], v[2:3]
	v_mov_b64_e32 v[82:83], v[2:3]
	v_mov_b64_e32 v[86:87], v[2:3]
	v_mov_b64_e32 v[90:91], v[2:3]
	v_mov_b64_e32 v[94:95], v[2:3]
	v_mov_b64_e32 v[98:99], v[2:3]
	v_mov_b64_e32 v[102:103], v[2:3]
	v_mov_b64_e32 v[106:107], v[2:3]
	v_mov_b64_e32 v[110:111], v[2:3]
	v_mov_b64_e32 v[114:115], v[2:3]
	v_mov_b64_e32 v[118:119], v[2:3]
	v_mov_b64_e32 v[122:123], v[2:3]
	v_mov_b64_e32 v[126:127], v[2:3]
	v_mov_b64_e32 v[130:131], v[2:3]
	s_barrier
	v_lshrrev_b32_e32 v232, 1, v0
	v_lshl_add_u32 v232, s14, 8, v232
	v_mul_u32_u24_e32 v232, 0x1800, v232
	v_and_b32_e32 v233, 1, v0
	v_lshlrev_b32_e32 v233, 7, v233
	v_lshl_add_u32 v233, s62, 8, v233
	v_add_u32_e32 v232, v232, v233
	v_add_u32_e32 v233, 0x800, v232
	global_load_ubyte v234, v232, s[68:69]
	global_load_ubyte v234, v232, s[68:69] offset:2048
	global_load_ubyte v234, v233, s[68:69] offset:2048
	s_branch .LBB0_729
